# retention item: K/V chunk loads batched with the 16 state loads (one round trip instead of five)
# speedup vs baseline: 1.0236x; 1.0032x over previous
; __device__ __forceinline__ float log_sigmoid(float x) { return -log1pf(expf(-x)); }
; __device__ __forceinline__ void m3_outputs(const KQ p_in, int e, bool ctx_full, unsigned char* smem, unsigned* scan_word) {
;     ...
;         if (!is_attn) {
;             const float lgf = log_sigmoid(dec[h]), lgb = log_sigmoid(dec[8 + h]);
;             __syncthreads();
.LBB0_960:
	v_add_u32_e32 v106, s7, v81
	s_bfe_u32 s6, s2, 0x30003
	s_mov_b64 s[0:1], -1
	s_andn2_b64 vcc, exec, s[36:37]
	v_ashrrev_i32_e32 v107, 31, v106
	v_lshlrev_b32_e32 v144, 1, v84
	s_cbranch_vccnz .LBB0_962
	s_lshl_b32 s0, s6, 2
	s_add_u32 s0, s73, s0
	s_addc_u32 s1, s64, 0
	v_mov_b64_e32 v[0:1], s[0:1]
	global_load_dword v2, v[0:1], off
	s_mov_b32 s0, 0xc2b17218
	global_load_dword v0, v[0:1], off offset:32
	s_mov_b32 s11, 0x3f2aaaab
	s_mov_b32 s12, 0x3f317218
	s_mov_b32 s1, 0x7f800000
	s_mov_b32 s10, 0x33800000
	s_lshl_b32 s80, s6, 7
	s_waitcnt lgkmcnt(0)
	s_barrier
	s_waitcnt vmcnt(2)
	s_waitcnt vmcnt(1)
	v_mul_f32_e32 v3, 0xbfb8aa3b, v2
	v_fma_f32 v4, v2, s42, -v3
	v_rndne_f32_e32 v5, v3
	v_fmac_f32_e32 v4, 0xb2a5705f, v2
	v_sub_f32_e32 v3, v3, v5
	v_add_f32_e32 v3, v3, v4
	v_exp_f32_e32 v3, v3
	v_cvt_i32_f32_e32 v4, v5
	v_cmp_nlt_f32_e32 vcc, s9, v2
	s_waitcnt vmcnt(0)
	v_mul_f32_e32 v1, 0xbfb8aa3b, v0
	v_ldexp_f32 v3, v3, v4
	v_cndmask_b32_e32 v3, 0, v3, vcc
	v_cmp_ngt_f32_e32 vcc, s0, v2
	s_nop 1
	v_cndmask_b32_e32 v16, v203, v3, vcc
	v_add_f32_e32 v4, 1.0, v16
	v_add_f32_e32 v2, -1.0, v4
	v_sub_f32_e32 v3, v2, v4
	v_add_f32_e32 v3, 1.0, v3
	v_sub_f32_e32 v2, v16, v2
	v_add_f32_e32 v5, v2, v3
	v_frexp_mant_f32_e32 v2, v4
	v_cmp_gt_f32_e32 vcc, s11, v2
	v_cvt_f64_f32_e32 v[2:3], v4
	v_frexp_exp_i32_f64_e32 v2, v[2:3]
	v_subbrev_co_u32_e32 v10, vcc, 0, v2, vcc
	v_sub_u32_e32 v2, 0, v10
	v_ldexp_f32 v3, v4, v2
	v_add_f32_e32 v4, -1.0, v3
	v_add_f32_e32 v6, 1.0, v3
	v_ldexp_f32 v2, v5, v2
	v_add_f32_e32 v5, 1.0, v4
	v_add_f32_e32 v7, -1.0, v6
	v_sub_f32_e32 v5, v3, v5
	v_sub_f32_e32 v3, v3, v7
	v_add_f32_e32 v5, v2, v5
	v_add_f32_e32 v2, v2, v3
	v_add_f32_e32 v11, v6, v2
	v_rcp_f32_e32 v13, v11
	v_sub_f32_e32 v3, v6, v11
	v_add_f32_e32 v12, v2, v3
	v_add_f32_e32 v3, v4, v5
	v_mul_f32_e32 v15, v3, v13
	v_sub_f32_e32 v2, v4, v3
	v_mul_f32_e32 v4, v11, v15
	v_fma_f32 v6, v15, v11, -v4
	v_fmac_f32_e32 v6, v15, v12
	v_add_f32_e32 v14, v5, v2
	v_add_f32_e32 v2, v4, v6
	v_sub_f32_e32 v5, v3, v2
	v_pk_add_f32 v[8:9], v[2:3], v[4:5] neg_lo:[0,1] neg_hi:[0,1]
	v_mov_b32_e32 v7, v2
	v_pk_add_f32 v[2:3], v[8:9], v[6:7] neg_lo:[0,1] neg_hi:[0,1]
	v_cmp_neq_f32_e32 vcc, s1, v16
	v_add_f32_e32 v3, v14, v3
	v_add_f32_e32 v2, v2, v3
	v_add_f32_e32 v3, v5, v2
	v_mul_f32_e32 v14, v13, v3
	v_mul_f32_e32 v4, v11, v14
	v_fma_f32 v6, v14, v11, -v4
	v_fmac_f32_e32 v6, v14, v12
	v_sub_f32_e32 v5, v5, v3
	v_add_f32_e32 v11, v2, v5
	v_add_f32_e32 v2, v4, v6
	v_sub_f32_e32 v5, v3, v2
	v_pk_add_f32 v[8:9], v[2:3], v[4:5] neg_lo:[0,1] neg_hi:[0,1]
	v_mov_b32_e32 v7, v2
	v_pk_add_f32 v[2:3], v[8:9], v[6:7] neg_lo:[0,1] neg_hi:[0,1]
	s_nop 0
	v_add_f32_e32 v3, v11, v3
	v_add_f32_e32 v2, v2, v3
	v_add_f32_e32 v3, v15, v14
	v_add_f32_e32 v2, v5, v2
	v_sub_f32_e32 v4, v3, v15
	v_mul_f32_e32 v2, v13, v2
	v_sub_f32_e32 v4, v14, v4
	v_add_f32_e32 v4, v4, v2
	v_add_f32_e32 v6, v3, v4
	v_mul_f32_e32 v7, v6, v6
	v_fmamk_f32 v2, v7, 0x3e9b6dac, v191
	v_fmaak_f32 v149, v7, v2, 0x3f2aaada
	v_cvt_f32_i32_e32 v2, v10
	v_sub_f32_e32 v3, v6, v3
	v_sub_f32_e32 v3, v4, v3
	v_ldexp_f32 v8, v3, 1
	v_mul_f32_e32 v3, v6, v7
	v_ldexp_f32 v5, v6, 1
	v_pk_mul_f32 v[6:7], v[2:3], v[148:149]
	s_nop 0
	v_fma_f32 v4, v2, s12, -v6
	v_fmac_f32_e32 v4, 0xb102e308, v2
	v_pk_add_f32 v[2:3], v[6:7], v[4:5]
	s_nop 0
	v_sub_f32_e32 v5, v3, v5
	v_sub_f32_e32 v5, v7, v5
	v_add_f32_e32 v9, v8, v5
	v_mov_b32_e32 v8, v6
	v_pk_add_f32 v[6:7], v[2:3], v[6:7] neg_lo:[0,1] neg_hi:[0,1]
	v_pk_add_f32 v[10:11], v[2:3], v[8:9]
	v_mov_b32_e32 v5, v2
	v_mov_b32_e32 v7, v11
	v_pk_add_f32 v[12:13], v[4:5], v[6:7] neg_lo:[0,1] neg_hi:[0,1]
	v_pk_add_f32 v[4:5], v[4:5], v[6:7]
	v_mov_b32_e32 v8, v9
	v_pk_add_f32 v[6:7], v[4:5], v[2:3] op_sel:[1,0] op_sel_hi:[0,1] neg_lo:[0,1] neg_hi:[0,1]
	v_pk_add_f32 v[14:15], v[10:11], v[6:7] op_sel_hi:[1,0] neg_lo:[0,1] neg_hi:[0,1]
	v_mov_b32_e32 v10, v11
	v_mov_b32_e32 v11, v5
	v_pk_mov_b32 v[6:7], v[2:3], v[6:7] op_sel:[1,0]
	v_mov_b32_e32 v9, v2
	v_pk_add_f32 v[6:7], v[10:11], v[6:7] neg_lo:[0,1] neg_hi:[0,1]
	v_mov_b32_e32 v14, v12
	v_pk_add_f32 v[2:3], v[8:9], v[6:7] neg_lo:[0,1] neg_hi:[0,1]
	v_mov_b32_e32 v13, v5
	v_pk_add_f32 v[6:7], v[14:15], v[2:3]
	s_nop 0
	v_pk_add_f32 v[8:9], v[6:7], v[6:7] op_sel:[0,1] op_sel_hi:[1,0]
	s_nop 0
	v_pk_add_f32 v[4:5], v[4:5], v[8:9] op_sel:[1,0] op_sel_hi:[0,1]
	v_mov_b32_e32 v7, v4
	v_pk_add_f32 v[10:11], v[6:7], v[12:13] neg_lo:[0,1] neg_hi:[0,1]
	v_mov_b32_e32 v3, v8
	v_sub_f32_e32 v5, v6, v10
	v_pk_add_f32 v[2:3], v[2:3], v[10:11] neg_lo:[0,1] neg_hi:[0,1]
	v_sub_f32_e32 v5, v12, v5
	v_add_f32_e32 v2, v2, v5
	v_add_f32_e32 v2, v2, v3
	v_add_f32_e32 v2, v4, v2
	v_cndmask_b32_e32 v2, v203, v2, vcc
	v_cmp_lt_f32_e64 vcc, |v16|, s10
	v_rndne_f32_e32 v3, v1
	s_nop 0
	v_cndmask_b32_e32 v26, v2, v16, vcc
	v_fma_f32 v2, v0, s42, -v1
	v_fmac_f32_e32 v2, 0xb2a5705f, v0
	v_sub_f32_e32 v1, v1, v3
	v_add_f32_e32 v1, v1, v2
	v_exp_f32_e32 v1, v1
	v_cvt_i32_f32_e32 v2, v3
	v_cmp_nlt_f32_e32 vcc, s9, v0
	v_ldexp_f32 v1, v1, v2
	s_nop 0
	v_cndmask_b32_e32 v1, 0, v1, vcc
	v_cmp_ngt_f32_e32 vcc, s0, v0
	s_nop 1
	v_cndmask_b32_e32 v14, v203, v1, vcc
	v_add_f32_e32 v2, 1.0, v14
	v_add_f32_e32 v0, -1.0, v2
	v_sub_f32_e32 v1, v0, v2
	v_add_f32_e32 v1, 1.0, v1
	v_sub_f32_e32 v0, v14, v0
	v_add_f32_e32 v3, v0, v1
	v_frexp_mant_f32_e32 v0, v2
	v_cmp_gt_f32_e32 vcc, s11, v0
	v_cvt_f64_f32_e32 v[0:1], v2
	v_frexp_exp_i32_f64_e32 v0, v[0:1]
	v_subbrev_co_u32_e32 v8, vcc, 0, v0, vcc
	v_sub_u32_e32 v0, 0, v8
	v_ldexp_f32 v1, v2, v0
	v_add_f32_e32 v2, -1.0, v1
	v_add_f32_e32 v4, 1.0, v1
	v_ldexp_f32 v0, v3, v0
	v_add_f32_e32 v3, 1.0, v2
	v_add_f32_e32 v5, -1.0, v4
; __device__ __forceinline__ float log_sigmoid(float x) { return -log1pf(expf(-x)); }
; __device__ __forceinline__ void m3_outputs(const KQ p_in, int e, bool ctx_full, unsigned char* smem, unsigned* scan_word) {
;     ...
;             for (int q = 0; q < 2; ++q) { const int idx = tid + 512 * q; const int r = idx >> 3, pc = idx & 7; const bf16_t* zr = Z + (size_t)(t0 + r) * INW + h * 64 + pc * 8;
;                 *(u32x4*)(Kt + r * 72 + pc * 8) = *(const u32x4*)(zr + 1792);
;                 const bf16x8 vv = *(const bf16x8*)(zr + 2304);
; #pragma unroll
;                 for (int j = 0; j < 8; ++j) Vt[(pc * 8 + j) * 136 + (r ^ (pc << 2))] = (bf16_t)vv[j]; }
;             const size_t so = ((size_t)(b * NCH + cidx) * 8 + h) * 4096;
;             {
;                 const int ee = tid & 63, d0 = (tid >> 6) * 8;
;                 float tf[8], tb[8];
; #pragma unroll
;                 for (int j = 0; j < 8; ++j) { tf[j] = TF[so + (d0 + j) * 64 + ee]; tb[j] = TB[so + (d0 + j) * 64 + ee]; }
	v_sub_f32_e32 v3, v1, v3
	v_sub_f32_e32 v1, v1, v5
	v_add_f32_e32 v3, v0, v3
	v_add_f32_e32 v0, v0, v1
	v_add_f32_e32 v9, v4, v0
	v_rcp_f32_e32 v11, v9
	v_sub_f32_e32 v1, v4, v9
	v_add_f32_e32 v10, v0, v1
	v_add_f32_e32 v1, v2, v3
	v_mul_f32_e32 v13, v1, v11
	v_sub_f32_e32 v0, v2, v1
	v_mul_f32_e32 v2, v9, v13
	v_fma_f32 v4, v13, v9, -v2
	v_fmac_f32_e32 v4, v13, v10
	v_add_f32_e32 v12, v3, v0
	v_add_f32_e32 v0, v2, v4
	v_sub_f32_e32 v3, v1, v0
	v_pk_add_f32 v[6:7], v[0:1], v[2:3] neg_lo:[0,1] neg_hi:[0,1]
	v_mov_b32_e32 v5, v0
	v_pk_add_f32 v[0:1], v[6:7], v[4:5] neg_lo:[0,1] neg_hi:[0,1]
	v_cmp_neq_f32_e32 vcc, s1, v14
	v_add_f32_e32 v1, v12, v1
	v_add_f32_e32 v0, v0, v1
	v_add_f32_e32 v1, v3, v0
	v_mul_f32_e32 v12, v11, v1
	v_mul_f32_e32 v2, v9, v12
	v_fma_f32 v4, v12, v9, -v2
	v_fmac_f32_e32 v4, v12, v10
	v_sub_f32_e32 v3, v3, v1
	v_add_f32_e32 v9, v0, v3
	v_add_f32_e32 v0, v2, v4
	v_sub_f32_e32 v3, v1, v0
	v_pk_add_f32 v[6:7], v[0:1], v[2:3] neg_lo:[0,1] neg_hi:[0,1]
	v_mov_b32_e32 v5, v0
	v_pk_add_f32 v[0:1], v[6:7], v[4:5] neg_lo:[0,1] neg_hi:[0,1]
	s_nop 0
	v_add_f32_e32 v1, v9, v1
	v_add_f32_e32 v0, v0, v1
	v_add_f32_e32 v1, v13, v12
	v_add_f32_e32 v0, v3, v0
	v_sub_f32_e32 v2, v1, v13
	v_mul_f32_e32 v0, v11, v0
	v_sub_f32_e32 v2, v12, v2
	v_add_f32_e32 v2, v2, v0
	v_add_f32_e32 v4, v1, v2
	v_mul_f32_e32 v5, v4, v4
	v_fmamk_f32 v0, v5, 0x3e9b6dac, v191
	v_fmaak_f32 v149, v5, v0, 0x3f2aaada
	v_cvt_f32_i32_e32 v0, v8
	v_sub_f32_e32 v1, v4, v1
	v_sub_f32_e32 v1, v2, v1
	v_ldexp_f32 v6, v1, 1
	v_mul_f32_e32 v1, v4, v5
	v_ldexp_f32 v3, v4, 1
	v_pk_mul_f32 v[4:5], v[0:1], v[148:149]
	s_nop 0
	v_fma_f32 v2, v0, s12, -v4
	v_fmac_f32_e32 v2, 0xb102e308, v0
	v_pk_add_f32 v[0:1], v[4:5], v[2:3]
	s_nop 0
	v_sub_f32_e32 v3, v1, v3
	v_sub_f32_e32 v3, v5, v3
	v_add_f32_e32 v7, v6, v3
	v_mov_b32_e32 v6, v4
	v_pk_add_f32 v[4:5], v[0:1], v[4:5] neg_lo:[0,1] neg_hi:[0,1]
	v_pk_add_f32 v[8:9], v[0:1], v[6:7]
	v_mov_b32_e32 v3, v0
	v_mov_b32_e32 v5, v9
	v_pk_add_f32 v[10:11], v[2:3], v[4:5] neg_lo:[0,1] neg_hi:[0,1]
	v_pk_add_f32 v[2:3], v[2:3], v[4:5]
	v_mov_b32_e32 v6, v7
	v_pk_add_f32 v[4:5], v[2:3], v[0:1] op_sel:[1,0] op_sel_hi:[0,1] neg_lo:[0,1] neg_hi:[0,1]
	v_pk_add_f32 v[12:13], v[8:9], v[4:5] op_sel_hi:[1,0] neg_lo:[0,1] neg_hi:[0,1]
	v_mov_b32_e32 v8, v9
	v_mov_b32_e32 v9, v3
	v_pk_mov_b32 v[4:5], v[0:1], v[4:5] op_sel:[1,0]
	v_mov_b32_e32 v7, v0
	v_pk_add_f32 v[4:5], v[8:9], v[4:5] neg_lo:[0,1] neg_hi:[0,1]
	v_mov_b32_e32 v12, v10
	v_pk_add_f32 v[0:1], v[6:7], v[4:5] neg_lo:[0,1] neg_hi:[0,1]
	v_mov_b32_e32 v11, v3
	v_pk_add_f32 v[4:5], v[12:13], v[0:1]
	s_nop 0
	v_pk_add_f32 v[6:7], v[4:5], v[4:5] op_sel:[0,1] op_sel_hi:[1,0]
	s_nop 0
	v_pk_add_f32 v[2:3], v[2:3], v[6:7] op_sel:[1,0] op_sel_hi:[0,1]
	v_mov_b32_e32 v5, v2
	v_pk_add_f32 v[8:9], v[4:5], v[10:11] neg_lo:[0,1] neg_hi:[0,1]
	v_mov_b32_e32 v1, v6
	v_sub_f32_e32 v3, v4, v8
	v_pk_add_f32 v[0:1], v[0:1], v[8:9] neg_lo:[0,1] neg_hi:[0,1]
	v_sub_f32_e32 v3, v10, v3
	v_add_f32_e32 v0, v0, v3
	v_add_f32_e32 v0, v0, v1
	v_add_f32_e32 v0, v2, v0
	v_cndmask_b32_e32 v0, v203, v0, vcc
	v_cmp_lt_f32_e64 vcc, |v14|, s10
	v_add_u32_e32 v2, s7, v114
	s_nop 0
	v_cndmask_b32_e32 v27, v0, v14, vcc
	v_lshl_add_u64 v[0:1], v[82:83], 0, s[80:81]
	v_mad_i64_i32 v[6:7], s[0:1], v2, s54, v[0:1]
	global_load_dwordx4 v[64:67], v[6:7], off offset:3584
	v_add_co_u32_e32 v2, vcc, s43, v6
	s_nop 1
	v_addc_co_u32_e32 v3, vcc, 0, v7, vcc
	global_load_dwordx4 v[68:71], v[2:3], off offset:512
	v_add_u32_e32 v2, s7, v115
	v_mad_i64_i32 v[4:5], s[0:1], v2, s54, v[0:1]
	global_load_dwordx4 v[72:75], v[4:5], off offset:3584
	v_add_co_u32_e32 v0, vcc, s43, v4
	s_nop 1
	v_addc_co_u32_e32 v1, vcc, 0, v5, vcc
	global_load_dwordx4 v[76:79], v[0:1], off offset:512
	s_mul_i32 s0, s5, 34
	s_add_i32 s0, s0, s8
	s_ashr_i32 s1, s0, 31
	s_lshl_b64 s[0:1], s[0:1], 15
	s_lshl_b32 s7, s6, 12
	s_or_b32 s0, s0, s7
	v_mov_b32_e32 v3, s1
	v_or_b32_e32 v2, s0, v80
	v_lshl_add_u64 v[0:1], v[2:3], 0, v[90:91]
	v_lshl_add_u64 v[6:7], v[2:3], 0, v[92:93]
	v_lshl_add_u64 v[10:11], v[2:3], 0, v[94:95]
	v_lshl_add_u64 v[14:15], v[2:3], 0, v[96:97]
	v_lshl_add_u64 v[18:19], v[2:3], 0, v[98:99]
	v_lshlrev_b64 v[0:1], 2, v[0:1]
	v_lshlrev_b64 v[6:7], 2, v[6:7]
	v_lshlrev_b64 v[10:11], 2, v[10:11]
	v_lshlrev_b64 v[14:15], 2, v[14:15]
	v_lshlrev_b64 v[18:19], 2, v[18:19]
	v_lshl_add_u64 v[22:23], v[2:3], 0, v[100:101]
	v_lshl_add_u64 v[28:29], v[2:3], 0, v[102:103]
	v_lshl_add_u64 v[2:3], v[2:3], 0, v[104:105]
	v_lshl_add_u64 v[4:5], s[92:93], 0, v[0:1]
	v_lshl_add_u64 v[8:9], s[92:93], 0, v[6:7]
	v_lshl_add_u64 v[6:7], s[94:95], 0, v[6:7]
	v_lshl_add_u64 v[12:13], s[92:93], 0, v[10:11]
	v_lshl_add_u64 v[10:11], s[94:95], 0, v[10:11]
	v_lshl_add_u64 v[16:17], s[92:93], 0, v[14:15]
	v_lshl_add_u64 v[14:15], s[94:95], 0, v[14:15]
	v_lshl_add_u64 v[20:21], s[92:93], 0, v[18:19]
	v_lshl_add_u64 v[18:19], s[94:95], 0, v[18:19]
	v_lshlrev_b64 v[22:23], 2, v[22:23]
	v_lshlrev_b64 v[28:29], 2, v[28:29]
	v_lshlrev_b64 v[2:3], 2, v[2:3]
	v_lshl_add_u64 v[0:1], s[94:95], 0, v[0:1]
	v_lshl_add_u64 v[24:25], s[92:93], 0, v[22:23]
	v_lshl_add_u64 v[22:23], s[94:95], 0, v[22:23]
	v_lshl_add_u64 v[30:31], s[92:93], 0, v[28:29]
	v_lshl_add_u64 v[28:29], s[94:95], 0, v[28:29]
	v_lshl_add_u64 v[32:33], s[92:93], 0, v[2:3]
	v_lshl_add_u64 v[2:3], s[94:95], 0, v[2:3]
	global_load_dword v8, v[8:9], off
	s_nop 0
	global_load_dword v4, v[4:5], off
	s_nop 0
	global_load_dword v5, v[16:17], off
	global_load_dword v9, v[12:13], off
	s_nop 0
	global_load_dword v12, v[24:25], off
	global_load_dword v13, v[20:21], off
	global_load_dword v16, v[32:33], off
	global_load_dword v17, v[30:31], off
	s_nop 0
	global_load_dword v6, v[6:7], off
	s_nop 0
	global_load_dword v7, v[0:1], off
	s_nop 0
	global_load_dword v14, v[14:15], off
	s_nop 0
	global_load_dword v10, v[10:11], off
	s_nop 0
	global_load_dword v11, v[22:23], off
	global_load_dword v15, v[18:19], off
	s_nop 0
	global_load_dword v18, v[2:3], off
	global_load_dword v19, v[28:29], off
	s_waitcnt lgkmcnt(0)
; __device__ __forceinline__ void m3_outputs(const KQ p_in, int e, bool ctx_full, unsigned char* smem, unsigned* scan_word) {
;     ...
;             for (int q = 0; q < 2; ++q) { const int idx = tid + 512 * q; const int r = idx >> 3, pc = idx & 7; const bf16_t* zr = Z + (size_t)(t0 + r) * INW + h * 64 + pc * 8;
;                 *(u32x4*)(Kt + r * 72 + pc * 8) = *(const u32x4*)(zr + 1792);
;                 const bf16x8 vv = *(const bf16x8*)(zr + 2304);
; #pragma unroll
;                 for (int j = 0; j < 8; ++j) Vt[(pc * 8 + j) * 136 + (r ^ (pc << 2))] = (bf16_t)vv[j]; }
;             const size_t so = ((size_t)(b * NCH + cidx) * 8 + h) * 4096;
;             {
;                 const int ee = tid & 63, d0 = (tid >> 6) * 8;
;                 float tf[8], tb[8];
; #pragma unroll
;                 for (int j = 0; j < 8; ++j) { tf[j] = TF[so + (d0 + j) * 64 + ee]; tb[j] = TB[so + (d0 + j) * 64 + ee]; }
;                 u32x4 wf4, wb4;
;                 wf4.x = pg8::cvt_pk_bf16(tf[0], tf[1]); wf4.y = pg8::cvt_pk_bf16(tf[2], tf[3]); wf4.z = pg8::cvt_pk_bf16(tf[4], tf[5]); wf4.w = pg8::cvt_pk_bf16(tf[6], tf[7]);
;                 wb4.x = pg8::cvt_pk_bf16(tb[0], tb[1]); wb4.y = pg8::cvt_pk_bf16(tb[2], tb[3]); wb4.z = pg8::cvt_pk_bf16(tb[4], tb[5]); wb4.w = pg8::cvt_pk_bf16(tb[6], tb[7]);
;                 *(u32x4*)(TfT + ee * 72 + d0) = wf4; *(u32x4*)(TbT + ee * 72 + d0) = wb4;
;             }
;             __builtin_amdgcn_sched_barrier(0);
;             bf16x8 qf[2], qff[2], qfb[2];
;             { const bf16_t* qr = Z + (size_t)(t0 + i) * INW + 512 + h * 64 + 8 * g4;
;               const float cf = __expf(lgf * (float)(i + 1)), cb = __expf(lgb * (float)(128 - i));
; #pragma unroll
;               for (int k2 = 0; k2 < 2; ++k2) { qf[k2] = *(const bf16x8*)(qr + 32 * k2);
;                   f32x4 a0, a1, b0, b1;
; #pragma unroll
;                   for (int j = 0; j < 4; ++j) { const float x0 = bf2f((bf16_t)qf[k2][j]), x1 = bf2f((bf16_t)qf[k2][4 + j]); a0[j] = x0 * cf; a1[j] = x1 * cf; b0[j] = x0 * cb; b1[j] = x1 * cb; }
;                   qff[k2] = pack8(a0, a1); qfb[k2] = pack8(b0, b1); } }
;             __builtin_amdgcn_sched_barrier(0);
;             __syncthreads();
; #pragma unroll
;             for (int m = 0; m < 4; ++m)
; #pragma unroll
;                 for (int k2 = 0; k2 < 2; ++k2) {
	s_waitcnt vmcnt(19) lgkmcnt(0)
	ds_write_b128 v158, v[64:67]
	s_waitcnt vmcnt(18)
	ds_write_b16 v159, v68 offset:18432
	ds_write_b16_d16_hi v159, v68 offset:18704
	ds_write_b16 v159, v69 offset:18976
	ds_write_b16_d16_hi v159, v69 offset:19248
	ds_write_b16 v159, v70 offset:19520
	ds_write_b16_d16_hi v159, v70 offset:19792
	ds_write_b16 v159, v71 offset:20064
	ds_write_b16_d16_hi v159, v71 offset:20336
	s_waitcnt vmcnt(17)
	ds_write_b128 v160, v[72:75]
	s_waitcnt vmcnt(16)
	ds_write_b16 v161, v76 offset:18432
	ds_write_b16_d16_hi v161, v76 offset:18704
	ds_write_b16 v161, v77 offset:18976
	ds_write_b16_d16_hi v161, v77 offset:19248
	ds_write_b16 v161, v78 offset:19520
	ds_write_b16_d16_hi v161, v78 offset:19792
	ds_write_b16 v161, v79 offset:20064
	ds_write_b16_d16_hi v161, v79 offset:20336
	s_waitcnt vmcnt(14)
	v_cvt_pk_bf16_f32 v0, v4, v8
	s_waitcnt vmcnt(12)
	v_cvt_pk_bf16_f32 v1, v9, v5
	s_waitcnt vmcnt(10)
	v_cvt_pk_bf16_f32 v2, v13, v12
	s_waitcnt vmcnt(8)
	v_cvt_pk_bf16_f32 v3, v17, v16
	s_waitcnt vmcnt(6)
	v_cvt_pk_bf16_f32 v4, v7, v6
	s_waitcnt vmcnt(4)
	v_cvt_pk_bf16_f32 v5, v10, v14
	s_waitcnt vmcnt(2)
	v_cvt_pk_bf16_f32 v6, v15, v11
	s_waitcnt vmcnt(0)
	v_cvt_pk_bf16_f32 v7, v19, v18
	ds_write_b128 v85, v[0:3] offset:35840
	ds_write_b128 v85, v[4:7] offset:45056
	v_mov_b64_e32 v[0:1], s[88:89]
	v_mad_i64_i32 v[0:1], s[0:1], v106, s54, v[0:1]
	v_lshl_add_u64 v[24:25], v[0:1], 0, s[80:81]
	v_lshl_add_u64 v[4:5], v[24:25], 0, v[144:145]
	global_load_dwordx4 v[0:3], v[4:5], off offset:1024
	v_mul_f32_e32 v6, v87, v26
	v_mul_f32_e32 v7, v110, v27
	v_mul_f32_e32 v6, 0xbfb8aa3b, v6
	v_mul_f32_e32 v7, 0xbfb8aa3b, v7
	v_exp_f32_e32 v6, v6
	v_exp_f32_e32 v7, v7
	s_waitcnt lgkmcnt(0)
	s_waitcnt vmcnt(0)
	v_lshlrev_b32_e32 v8, 16, v0
	v_lshlrev_b32_e32 v9, 16, v2
	v_and_b32_e32 v10, 0xffff0000, v0
	v_and_b32_e32 v11, 0xffff0000, v2
	v_lshlrev_b32_e32 v12, 16, v1
	v_lshlrev_b32_e32 v13, 16, v3
	v_and_b32_e32 v14, 0xffff0000, v1
	v_and_b32_e32 v15, 0xffff0000, v3
	v_mul_f32_e32 v16, v6, v8
	v_mul_f32_e32 v18, v6, v9
	v_mul_f32_e32 v17, v6, v10
	v_mul_f32_e32 v19, v6, v11
	v_mul_f32_e32 v20, v6, v12
	v_mul_f32_e32 v21, v6, v13
	v_mul_f32_e32 v22, v6, v14
	v_mul_f32_e32 v23, v6, v15
	v_mul_f32_e32 v8, v7, v8
	v_mul_f32_e32 v9, v7, v9
	v_mul_f32_e32 v10, v7, v10
	v_mul_f32_e32 v11, v7, v11
	v_mul_f32_e32 v12, v7, v12
	v_mul_f32_e32 v13, v7, v13
	v_mul_f32_e32 v14, v7, v14
	v_mul_f32_e32 v15, v7, v15
	v_cvt_pk_bf16_f32 v16, v16, v17
	v_cvt_pk_bf16_f32 v17, v20, v22
	v_cvt_pk_bf16_f32 v18, v18, v19
	v_cvt_pk_bf16_f32 v19, v21, v23
	v_cvt_pk_bf16_f32 v28, v8, v10
	v_cvt_pk_bf16_f32 v29, v12, v14
	v_cvt_pk_bf16_f32 v30, v9, v11
	v_cvt_pk_bf16_f32 v31, v13, v15
	global_load_dwordx4 v[20:23], v[4:5], off offset:1088
	s_waitcnt lgkmcnt(0)
	s_waitcnt vmcnt(0)
	v_and_b32_e32 v8, 0xffff0000, v20
	v_and_b32_e32 v9, 0xffff0000, v22
	v_lshlrev_b32_e32 v10, 16, v21
	v_lshlrev_b32_e32 v11, 16, v23
	v_and_b32_e32 v12, 0xffff0000, v21
	v_lshlrev_b32_e32 v4, 16, v20
	v_lshlrev_b32_e32 v5, 16, v22
	v_and_b32_e32 v13, 0xffff0000, v23
	v_mul_f32_e32 v32, v6, v8
	v_mul_f32_e32 v34, v6, v9
	v_mul_f32_e32 v33, v6, v10
	v_mul_f32_e32 v35, v6, v11
	v_mul_f32_e32 v36, v6, v12
	v_mul_f32_e32 v14, v6, v4
	v_mul_f32_e32 v15, v6, v5
	v_mul_f32_e32 v4, v7, v4
	v_mul_f32_e32 v5, v7, v5
	v_mul_f32_e32 v8, v7, v8
	v_mul_f32_e32 v9, v7, v9
	v_mul_f32_e32 v10, v7, v10
	v_mul_f32_e32 v11, v7, v11
	v_mul_f32_e32 v6, v6, v13
	v_mul_f32_e32 v12, v7, v12
	v_mul_f32_e32 v7, v7, v13
	v_cvt_pk_bf16_f32 v32, v14, v32
	v_cvt_pk_bf16_f32 v33, v33, v36
	v_cvt_pk_bf16_f32 v34, v15, v34
	v_cvt_pk_bf16_f32 v35, v35, v6
	v_cvt_pk_bf16_f32 v36, v4, v8
	v_cvt_pk_bf16_f32 v37, v10, v12
	v_cvt_pk_bf16_f32 v38, v5, v9
	v_cvt_pk_bf16_f32 v39, v11, v7
	s_barrier
	ds_read_b128 v[4:7], v116 offset:35840
	ds_read_b128 v[8:11], v116 offset:45056
	s_waitcnt lgkmcnt(1)
	v_mfma_f32_16x16x32_bf16 v[4:7], v[4:7], v[16:19], 0
	s_waitcnt lgkmcnt(0)
	v_mfma_f32_16x16x32_bf16 v[4:7], v[8:11], v[28:31], v[4:7]
	ds_read_b128 v[8:11], v116 offset:35904
	s_waitcnt lgkmcnt(0)
	v_mfma_f32_16x16x32_bf16 v[4:7], v[8:11], v[32:35], v[4:7]
	ds_read_b128 v[8:11], v116 offset:45120
	s_waitcnt lgkmcnt(0)
	v_mfma_f32_16x16x32_bf16 v[4:7], v[8:11], v[36:39], v[4:7]
	ds_read_b128 v[8:11], v116 offset:38144
	ds_read_b128 v[12:15], v116 offset:47360
	s_waitcnt lgkmcnt(1)
	v_mfma_f32_16x16x32_bf16 v[8:11], v[8:11], v[16:19], 0
	s_waitcnt lgkmcnt(0)
	v_mfma_f32_16x16x32_bf16 v[8:11], v[12:15], v[28:31], v[8:11]
	ds_read_b128 v[12:15], v116 offset:38208
	s_waitcnt lgkmcnt(0)
	v_mfma_f32_16x16x32_bf16 v[8:11], v[12:15], v[32:35], v[8:11]
	ds_read_b128 v[12:15], v116 offset:47424
	s_waitcnt lgkmcnt(0)
	v_mfma_f32_16x16x32_bf16 v[8:11], v[12:15], v[36:39], v[8:11]
	ds_read_b128 v[12:15], v116 offset:40448
	ds_read_b128 v[40:43], v116 offset:49664
	s_waitcnt lgkmcnt(1)
	v_mfma_f32_16x16x32_bf16 v[12:15], v[12:15], v[16:19], 0
	s_waitcnt lgkmcnt(0)
	v_mfma_f32_16x16x32_bf16 v[12:15], v[40:43], v[28:31], v[12:15]
	ds_read_b128 v[40:43], v116 offset:40512
	s_waitcnt lgkmcnt(0)
	v_mfma_f32_16x16x32_bf16 v[12:15], v[40:43], v[32:35], v[12:15]
	ds_read_b128 v[40:43], v116 offset:49728
	s_waitcnt lgkmcnt(0)
	v_mfma_f32_16x16x32_bf16 v[12:15], v[40:43], v[36:39], v[12:15]
	ds_read_b128 v[40:43], v116 offset:42752
	s_waitcnt lgkmcnt(0)
	v_mfma_f32_16x16x32_bf16 v[16:19], v[40:43], v[16:19], 0
	ds_read_b128 v[40:43], v116 offset:51968
	s_waitcnt lgkmcnt(0)
	v_mfma_f32_16x16x32_bf16 v[16:19], v[40:43], v[28:31], v[16:19]
	ds_read_b128 v[28:31], v116 offset:42816
	s_waitcnt lgkmcnt(0)
; __device__ __forceinline__ void m3_outputs(const KQ p_in, int e, bool ctx_full, unsigned char* smem, unsigned* scan_word) {
;     ...
;             const float lf2 = lgf * 1.44269504f, lb2 = lgb * 1.44269504f; const int di = i - 4 * g4;
;             const float bfw = lf2 * (float)di, bbw = -lb2 * (float)di;
;             f32x4 st[8];
; #pragma unroll
;             for (int mt = 0; mt < 8; ++mt) {
;                 f32x4 a = (f32x4){0.f, 0.f, 0.f, 0.f};
; #pragma unroll
;                 for (int k2 = 0; k2 < 2; ++k2) { const bf16x8 kf = *(const bf16x8*)(Kt + (16 * mt + ln) * 72 + 32 * k2 + 8 * g4); a = __builtin_amdgcn_mfma_f32_16x16x32_bf16(kf, qf[k2], a, 0, 0, 0); }
; #pragma unroll
;                 for (int rg = 0; rg < 4; ++rg) { const int cc = 16 * mt + rg; const int df = di - cc;
;                     const float arg = (df > 0) ? fmaf(-lf2, (float)cc, bfw) : fmaf(lb2, (float)cc, bbw);
;                     float wgt = __builtin_amdgcn_exp2f(arg); wgt = (df == 0) ? 2.0f : wgt;
;                     a[rg] *= wgt; }
;                 st[mt] = a;
;                 __builtin_amdgcn_sched_barrier(0);
;             }
	v_mfma_f32_16x16x32_bf16 v[16:19], v[28:31], v[32:35], v[16:19]
	ds_read_b128 v[28:31], v116 offset:52032
	s_waitcnt lgkmcnt(0)
	v_mfma_f32_16x16x32_bf16 v[16:19], v[28:31], v[36:39], v[16:19]
	v_add_u32_e32 v33, v111, v117
	ds_read_b128 v[34:37], v33
	ds_read_b128 v[38:41], v33 offset:64
	v_mul_f32_e32 v28, 0xbfb8aa3b, v26
	v_mul_f32_e32 v26, 0xbfb8aa3b, v27
	v_mul_f32_e32 v27, v28, v112
	v_mul_f32_e64 v29, v112, -v26
	v_readlane_b32 s0, v253, 41
	v_fmamk_f32 v30, v28, 0x80000000, v27
	v_fma_f32 v31, 0, v26, v29
	v_readlane_b32 s1, v253, 42
	s_waitcnt lgkmcnt(1)
	v_mfma_f32_16x16x32_bf16 v[34:37], v[34:37], v[0:3], 0
	v_fma_f32 v32, v112, -v26, v26
	v_cndmask_b32_e64 v30, v31, v30, s[0:1]
	v_exp_f32_e32 v30, v30
	v_readlane_b32 s0, v253, 43
	v_readlane_b32 s1, v253, 44
	v_fma_f32 v31, v28, v112, -v28
	s_waitcnt lgkmcnt(0)
	v_mfma_f32_16x16x32_bf16 v[34:37], v[38:41], v[20:23], v[34:37]
	v_cndmask_b32_e64 v30, v30, 2.0, s[0:1]
	v_readlane_b32 s0, v253, 45
	v_readlane_b32 s1, v253, 46
	s_nop 1
	v_cndmask_b32_e64 v31, v32, v31, s[0:1]
	v_exp_f32_e32 v31, v31
	v_readlane_b32 s0, v253, 47
	v_readlane_b32 s1, v253, 48
	v_mul_f32_e32 v30, v30, v34
	v_fma_f32 v32, -2.0, v28, v27
	v_cndmask_b32_e64 v31, v31, 2.0, s[0:1]
	v_readlane_b32 s0, v253, 49
	v_fma_f32 v34, 2.0, v26, v29
	v_readlane_b32 s1, v253, 50
	v_mul_f32_e32 v31, v31, v35
	v_fmamk_f32 v35, v26, 0x40400000, v29
	v_cndmask_b32_e64 v32, v34, v32, s[0:1]
	v_exp_f32_e32 v32, v32
	v_readlane_b32 s0, v253, 51
	v_readlane_b32 s1, v253, 52
	v_fmamk_f32 v34, v28, 0xc0400000, v27
	s_nop 0
	v_cndmask_b32_e64 v32, v32, 2.0, s[0:1]
	v_readlane_b32 s0, v253, 53
	v_readlane_b32 s1, v253, 54
	v_mul_f32_e32 v32, v32, v36
	s_nop 0
	v_cndmask_b32_e64 v34, v35, v34, s[0:1]
	v_exp_f32_e32 v34, v34
	v_readlane_b32 s0, v253, 55
	v_readlane_b32 s1, v253, 56
	s_nop 1
	v_cndmask_b32_e64 v34, v34, 2.0, s[0:1]
	v_mul_f32_e32 v34, v34, v37
	ds_read_b128 v[36:39], v33 offset:2304
	ds_read_b128 v[40:43], v33 offset:2368
	v_readlane_b32 s0, v253, 57
	v_fmamk_f32 v35, v28, 0xc1800000, v27
	v_readlane_b32 s1, v253, 58
	s_waitcnt lgkmcnt(1)
	v_mfma_f32_16x16x32_bf16 v[36:39], v[36:39], v[0:3], 0
	s_waitcnt lgkmcnt(0)
	v_mfma_f32_16x16x32_bf16 v[36:39], v[40:43], v[20:23], v[36:39]
	v_fmamk_f32 v40, v26, 0x41800000, v29
	v_cndmask_b32_e64 v35, v40, v35, s[0:1]
	v_exp_f32_e32 v35, v35
	v_readlane_b32 s0, v253, 59
	v_readlane_b32 s1, v253, 60
	v_fmamk_f32 v40, v26, 0x41880000, v29
	s_nop 0
	v_cndmask_b32_e64 v35, v35, 2.0, s[0:1]
	v_readlane_b32 s0, v253, 61
	v_mul_f32_e32 v35, v35, v36
	v_fmamk_f32 v36, v28, 0xc1880000, v27
	v_readlane_b32 s1, v253, 62
	s_nop 1
	v_cndmask_b32_e64 v36, v40, v36, s[0:1]
	v_exp_f32_e32 v36, v36
	v_readlane_b32 s0, v253, 63
	v_readlane_b32 s1, v254, 0
	v_fmamk_f32 v40, v26, 0x41900000, v29
	s_nop 0
	v_cndmask_b32_e64 v36, v36, 2.0, s[0:1]
	v_readlane_b32 s0, v254, 1
	v_mul_f32_e32 v36, v36, v37
	v_fmamk_f32 v37, v28, 0xc1900000, v27
	v_readlane_b32 s1, v254, 2
	s_nop 1
	v_cndmask_b32_e64 v37, v40, v37, s[0:1]
	v_exp_f32_e32 v37, v37
	v_readlane_b32 s0, v254, 3
	v_readlane_b32 s1, v254, 4
	v_fmamk_f32 v40, v26, 0x41980000, v29
	s_nop 0
	v_cndmask_b32_e64 v37, v37, 2.0, s[0:1]
	v_readlane_b32 s0, v254, 5
	v_mul_f32_e32 v38, v37, v38
	v_fmamk_f32 v37, v28, 0xc1980000, v27
	v_readlane_b32 s1, v254, 6
	s_nop 1
	v_cndmask_b32_e64 v37, v40, v37, s[0:1]
	v_exp_f32_e32 v37, v37
	v_readlane_b32 s0, v254, 7
	v_readlane_b32 s1, v254, 8
	s_nop 1
	v_cndmask_b32_e64 v37, v37, 2.0, s[0:1]
	v_mul_f32_e32 v40, v37, v39
	ds_read_b128 v[42:45], v33 offset:4608
	ds_read_b128 v[46:49], v33 offset:4672
	v_readlane_b32 s0, v254, 9
	v_fmamk_f32 v37, v28, 0xc2000000, v27
	v_fmamk_f32 v39, v26, 0x42000000, v29
	v_readlane_b32 s1, v254, 10
	v_fmamk_f32 v41, v26, 0x42040000, v29
	s_waitcnt lgkmcnt(1)
	v_mfma_f32_16x16x32_bf16 v[42:45], v[42:45], v[0:3], 0
	v_cndmask_b32_e64 v37, v39, v37, s[0:1]
	v_exp_f32_e32 v37, v37
	v_readlane_b32 s0, v254, 11
	v_readlane_b32 s1, v254, 12
	v_fmamk_f32 v39, v28, 0xc2040000, v27
	s_waitcnt lgkmcnt(0)
	v_mfma_f32_16x16x32_bf16 v[42:45], v[46:49], v[20:23], v[42:45]
	v_cndmask_b32_e64 v37, v37, 2.0, s[0:1]
	v_readlane_b32 s0, v254, 13
	v_readlane_b32 s1, v254, 14
	s_nop 1
	v_cndmask_b32_e64 v39, v41, v39, s[0:1]
	v_exp_f32_e32 v39, v39
	v_readlane_b32 s0, v254, 15
	v_readlane_b32 s1, v254, 16
	v_mul_f32_e32 v37, v37, v42
	v_fmamk_f32 v41, v28, 0xc2080000, v27
	v_cndmask_b32_e64 v39, v39, 2.0, s[0:1]
	v_readlane_b32 s0, v254, 17
	v_fmamk_f32 v42, v26, 0x42080000, v29
	v_readlane_b32 s1, v254, 18
	v_mul_f32_e32 v39, v39, v43
	v_fmamk_f32 v43, v26, 0x420c0000, v29
	v_cndmask_b32_e64 v41, v42, v41, s[0:1]
	v_exp_f32_e32 v41, v41
	v_readlane_b32 s0, v254, 19
	v_readlane_b32 s1, v254, 20
	v_fmamk_f32 v42, v28, 0xc20c0000, v27
	s_nop 0
	v_cndmask_b32_e64 v41, v41, 2.0, s[0:1]
	v_readlane_b32 s0, v254, 21
	v_readlane_b32 s1, v254, 22
	v_mul_f32_e32 v41, v41, v44
	s_nop 0
	v_cndmask_b32_e64 v42, v43, v42, s[0:1]
	v_exp_f32_e32 v42, v42
	v_readlane_b32 s0, v254, 23
	v_readlane_b32 s1, v254, 24
	s_nop 1
	v_cndmask_b32_e64 v42, v42, 2.0, s[0:1]
	v_mul_f32_e32 v42, v42, v45
	ds_read_b128 v[44:47], v33 offset:6912
	ds_read_b128 v[48:51], v33 offset:6976
	v_readlane_b32 s0, v254, 25
	v_fmamk_f32 v43, v28, 0xc2400000, v27
	v_readlane_b32 s1, v254, 26
	s_waitcnt lgkmcnt(1)
	v_mfma_f32_16x16x32_bf16 v[44:47], v[44:47], v[0:3], 0
	s_waitcnt lgkmcnt(0)
; __device__ __forceinline__ void m3_outputs(const KQ p_in, int e, bool ctx_full, unsigned char* smem, unsigned* scan_word) {
;     ...
;             for (int mt = 0; mt < 8; ++mt) {
;                 f32x4 a = (f32x4){0.f, 0.f, 0.f, 0.f};
; #pragma unroll
;                 for (int k2 = 0; k2 < 2; ++k2) { const bf16x8 kf = *(const bf16x8*)(Kt + (16 * mt + ln) * 72 + 32 * k2 + 8 * g4); a = __builtin_amdgcn_mfma_f32_16x16x32_bf16(kf, qf[k2], a, 0, 0, 0); }
; #pragma unroll
;                 for (int rg = 0; rg < 4; ++rg) { const int cc = 16 * mt + rg; const int df = di - cc;
;                     const float arg = (df > 0) ? fmaf(-lf2, (float)cc, bfw) : fmaf(lb2, (float)cc, bbw);
;                     float wgt = __builtin_amdgcn_exp2f(arg); wgt = (df == 0) ? 2.0f : wgt;
;                     a[rg] *= wgt; }
;                 st[mt] = a;
;                 __builtin_amdgcn_sched_barrier(0);
;             }
	v_mfma_f32_16x16x32_bf16 v[44:47], v[48:51], v[20:23], v[44:47]
	v_fmamk_f32 v48, v26, 0x42400000, v29
	v_cndmask_b32_e64 v43, v48, v43, s[0:1]
	v_exp_f32_e32 v43, v43
	v_readlane_b32 s0, v254, 27
	v_readlane_b32 s1, v254, 28
	v_fmamk_f32 v48, v26, 0x42440000, v29
	s_nop 0
	v_cndmask_b32_e64 v43, v43, 2.0, s[0:1]
	v_readlane_b32 s0, v254, 29
	v_mul_f32_e32 v43, v43, v44
	v_fmamk_f32 v44, v28, 0xc2440000, v27
	v_readlane_b32 s1, v254, 30
	s_nop 1
	v_cndmask_b32_e64 v44, v48, v44, s[0:1]
	v_exp_f32_e32 v44, v44
	v_readlane_b32 s0, v254, 31
	v_readlane_b32 s1, v254, 32
	v_fmamk_f32 v48, v26, 0x42480000, v29
	s_nop 0
	v_cndmask_b32_e64 v44, v44, 2.0, s[0:1]
	v_readlane_b32 s0, v254, 33
	v_mul_f32_e32 v44, v44, v45
	v_fmamk_f32 v45, v28, 0xc2480000, v27
	v_readlane_b32 s1, v254, 34
	s_nop 1
	v_cndmask_b32_e64 v45, v48, v45, s[0:1]
	v_exp_f32_e32 v45, v45
	v_readlane_b32 s0, v254, 35
	v_readlane_b32 s1, v254, 36
	v_fmamk_f32 v48, v26, 0x424c0000, v29
	s_nop 0
	v_cndmask_b32_e64 v45, v45, 2.0, s[0:1]
	v_readlane_b32 s0, v254, 37
	v_mul_f32_e32 v45, v45, v46
	v_fmamk_f32 v46, v28, 0xc24c0000, v27
	v_readlane_b32 s1, v254, 38
	s_nop 1
	v_cndmask_b32_e64 v46, v48, v46, s[0:1]
	v_exp_f32_e32 v46, v46
	v_readlane_b32 s0, v254, 39
	v_readlane_b32 s1, v254, 40
	s_nop 1
	v_cndmask_b32_e64 v46, v46, 2.0, s[0:1]
	v_mul_f32_e32 v54, v46, v47
	ds_read_b128 v[46:49], v33 offset:9216
	ds_read_b128 v[50:53], v33 offset:9280
	v_readlane_b32 s0, v254, 41
	v_readlane_b32 s1, v254, 42
	s_waitcnt lgkmcnt(1)
	v_mfma_f32_16x16x32_bf16 v[46:49], v[46:49], v[0:3], 0
	s_waitcnt lgkmcnt(0)
	v_mfma_f32_16x16x32_bf16 v[46:49], v[50:53], v[20:23], v[46:49]
	v_fmamk_f32 v50, v28, 0xc2800000, v27
	v_fmamk_f32 v51, v26, 0x42800000, v29
	v_cndmask_b32_e64 v50, v51, v50, s[0:1]
	v_exp_f32_e32 v50, v50
	v_readlane_b32 s0, v254, 43
	v_readlane_b32 s1, v254, 44
	s_nop 1
	v_cndmask_b32_e64 v50, v50, 2.0, s[0:1]
	v_readlane_b32 s0, v254, 45
	v_mul_f32_e32 v55, v50, v46
	v_fmamk_f32 v46, v28, 0xc2820000, v27
	v_fmamk_f32 v50, v26, 0x42820000, v29
	v_readlane_b32 s1, v254, 46
	s_nop 1
	v_cndmask_b32_e64 v46, v50, v46, s[0:1]
	v_exp_f32_e32 v46, v46
	v_readlane_b32 s0, v254, 47
	v_readlane_b32 s1, v254, 48
	s_nop 1
	v_cndmask_b32_e64 v46, v46, 2.0, s[0:1]
	v_readlane_b32 s0, v254, 49
	v_mul_f32_e32 v56, v46, v47
	v_fmamk_f32 v46, v28, 0xc2840000, v27
	v_fmamk_f32 v47, v26, 0x42840000, v29
	v_readlane_b32 s1, v254, 50
	s_nop 1
	v_cndmask_b32_e64 v46, v47, v46, s[0:1]
	v_exp_f32_e32 v46, v46
	v_readlane_b32 s0, v254, 51
	v_readlane_b32 s1, v254, 52
	v_fmamk_f32 v47, v26, 0x42860000, v29
	s_nop 0
	v_cndmask_b32_e64 v46, v46, 2.0, s[0:1]
	v_readlane_b32 s0, v254, 53
	v_mul_f32_e32 v57, v46, v48
	v_fmamk_f32 v46, v28, 0xc2860000, v27
	v_readlane_b32 s1, v254, 54
	s_nop 1
	v_cndmask_b32_e64 v46, v47, v46, s[0:1]
	v_exp_f32_e32 v46, v46
	v_readlane_b32 s0, v254, 55
	v_readlane_b32 s1, v254, 56
	s_nop 1
	v_cndmask_b32_e64 v46, v46, 2.0, s[0:1]
	v_mul_f32_e32 v58, v46, v49
	ds_read_b128 v[46:49], v33 offset:11520
	ds_read_b128 v[50:53], v33 offset:11584
	v_readlane_b32 s0, v254, 57
	v_readlane_b32 s1, v254, 58
	s_waitcnt lgkmcnt(1)
	v_mfma_f32_16x16x32_bf16 v[46:49], v[46:49], v[0:3], 0
	s_waitcnt lgkmcnt(0)
	v_mfma_f32_16x16x32_bf16 v[46:49], v[50:53], v[20:23], v[46:49]
	v_fmamk_f32 v50, v28, 0xc2a00000, v27
	v_fmamk_f32 v51, v26, 0x42a00000, v29
	v_cndmask_b32_e64 v50, v51, v50, s[0:1]
	v_exp_f32_e32 v50, v50
	v_readlane_b32 s0, v254, 59
	v_readlane_b32 s1, v254, 60
	s_nop 1
	v_cndmask_b32_e64 v50, v50, 2.0, s[0:1]
	v_readlane_b32 s0, v254, 61
	v_mul_f32_e32 v59, v50, v46
	v_fmamk_f32 v46, v28, 0xc2a20000, v27
	v_fmamk_f32 v50, v26, 0x42a20000, v29
	v_readlane_b32 s1, v254, 62
	s_nop 1
	v_cndmask_b32_e64 v46, v50, v46, s[0:1]
	v_exp_f32_e32 v46, v46
	v_readlane_b32 s0, v254, 63
	v_readlane_b32 s1, v255, 0
	s_nop 1
	v_cndmask_b32_e64 v46, v46, 2.0, s[0:1]
	v_readlane_b32 s0, v255, 1
	v_mul_f32_e32 v60, v46, v47
	v_fmamk_f32 v46, v28, 0xc2a40000, v27
	v_fmamk_f32 v47, v26, 0x42a40000, v29
	v_readlane_b32 s1, v255, 2
	s_nop 1
	v_cndmask_b32_e64 v46, v47, v46, s[0:1]
	v_exp_f32_e32 v46, v46
	v_readlane_b32 s0, v255, 3
	v_readlane_b32 s1, v255, 4
	v_fmamk_f32 v47, v26, 0x42a60000, v29
	s_nop 0
	v_cndmask_b32_e64 v46, v46, 2.0, s[0:1]
	v_readlane_b32 s0, v255, 5
	v_mul_f32_e32 v61, v46, v48
	v_fmamk_f32 v46, v28, 0xc2a60000, v27
	v_readlane_b32 s1, v255, 6
	s_nop 1
	v_cndmask_b32_e64 v46, v47, v46, s[0:1]
	v_exp_f32_e32 v46, v46
	v_readlane_b32 s0, v255, 7
	v_readlane_b32 s1, v255, 8
	s_nop 1
	v_cndmask_b32_e64 v46, v46, 2.0, s[0:1]
	v_mul_f32_e32 v62, v46, v49
	ds_read_b128 v[46:49], v33 offset:13824
	ds_read_b128 v[50:53], v33 offset:13888
	v_readlane_b32 s0, v255, 9
	v_readlane_b32 s1, v255, 10
	s_waitcnt lgkmcnt(1)
	v_mfma_f32_16x16x32_bf16 v[46:49], v[46:49], v[0:3], 0
	s_waitcnt lgkmcnt(0)
	v_mfma_f32_16x16x32_bf16 v[46:49], v[50:53], v[20:23], v[46:49]
	v_fmamk_f32 v50, v28, 0xc2c00000, v27
	v_fmamk_f32 v51, v26, 0x42c00000, v29
	v_cndmask_b32_e64 v50, v51, v50, s[0:1]
	v_exp_f32_e32 v50, v50
	v_readlane_b32 s0, v255, 11
	v_readlane_b32 s1, v255, 12
	v_fmamk_f32 v51, v26, 0x42c20000, v29
	s_nop 0
	v_cndmask_b32_e64 v50, v50, 2.0, s[0:1]
	v_readlane_b32 s0, v255, 13
	v_mul_f32_e32 v50, v50, v46
	v_fmamk_f32 v46, v28, 0xc2c20000, v27
	v_readlane_b32 s1, v255, 14
	s_nop 1
	v_cndmask_b32_e64 v46, v51, v46, s[0:1]
	v_exp_f32_e32 v46, v46
	v_readlane_b32 s0, v255, 15
	v_readlane_b32 s1, v255, 16
	s_nop 1
	v_cndmask_b32_e64 v46, v46, 2.0, s[0:1]
	v_readlane_b32 s0, v255, 17
	v_mul_f32_e32 v51, v46, v47
	v_fmamk_f32 v46, v28, 0xc2c40000, v27
	v_fmamk_f32 v47, v26, 0x42c40000, v29
	v_readlane_b32 s1, v255, 18
	s_nop 1
	v_cndmask_b32_e64 v46, v47, v46, s[0:1]
	v_exp_f32_e32 v46, v46
	v_readlane_b32 s0, v255, 19
	v_readlane_b32 s1, v255, 20
	v_fmamk_f32 v47, v26, 0x42c60000, v29
	s_nop 0
	v_cndmask_b32_e64 v46, v46, 2.0, s[0:1]
	v_readlane_b32 s0, v255, 21
	v_mul_f32_e32 v52, v46, v48
	v_fmamk_f32 v46, v28, 0xc2c60000, v27
	v_readlane_b32 s1, v255, 22
	s_nop 1
	v_cndmask_b32_e64 v46, v47, v46, s[0:1]
	v_exp_f32_e32 v46, v46
	v_readlane_b32 s0, v255, 23
	v_readlane_b32 s1, v255, 24
	s_nop 1
	v_cndmask_b32_e64 v46, v46, 2.0, s[0:1]
	v_mul_f32_e32 v53, v46, v49
	ds_read_b128 v[46:49], v33 offset:16128
	s_waitcnt lgkmcnt(0)
; __device__ __forceinline__ void m3_outputs(const KQ p_in, int e, bool ctx_full, unsigned char* smem, unsigned* scan_word) {
;     ...
;             for (int mt = 0; mt < 8; ++mt) {
;                 f32x4 a = (f32x4){0.f, 0.f, 0.f, 0.f};
; #pragma unroll
;                 for (int k2 = 0; k2 < 2; ++k2) { const bf16x8 kf = *(const bf16x8*)(Kt + (16 * mt + ln) * 72 + 32 * k2 + 8 * g4); a = __builtin_amdgcn_mfma_f32_16x16x32_bf16(kf, qf[k2], a, 0, 0, 0); }
; #pragma unroll
;                 for (int rg = 0; rg < 4; ++rg) { const int cc = 16 * mt + rg; const int df = di - cc;
;                     const float arg = (df > 0) ? fmaf(-lf2, (float)cc, bfw) : fmaf(lb2, (float)cc, bbw);
;                     float wgt = __builtin_amdgcn_exp2f(arg); wgt = (df == 0) ? 2.0f : wgt;
;                     a[rg] *= wgt; }
;                 st[mt] = a;
;                 __builtin_amdgcn_sched_barrier(0);
;             }
; #pragma unroll
;             for (int ks = 0; ks < 4; ++ks) {
;                 const bf16x8 pfr = pack8(st[2 * ks], st[2 * ks + 1]);
; #pragma unroll
;                 for (int m = 0; m < 4; ++m) {
;                     const int vrow = 16 * m + ln; const int kx = (32 * ks + 4 * g4) ^ (((vrow >> 3) & 7) << 2);
;                     const bf16_t* vr = Vt + vrow * 136;
;                     const bf16x4 v0 = *(const bf16x4*)(vr + kx), v1 = *(const bf16x4*)(vr + (kx ^ 16));
;                     const bf16x8 vf = __builtin_shufflevector(v0, v1, 0, 1, 2, 3, 4, 5, 6, 7);
;                     O[m] = __builtin_amdgcn_mfma_f32_16x16x32_bf16(vf, pfr, O[m], 0, 0, 0);
;                 }
;                 __builtin_amdgcn_sched_barrier(0);
;             }
;             float ss = 0.f;
; #pragma unroll
;             for (int m = 0; m < 4; ++m)
; #pragma unroll
;                 for (int rg = 0; rg < 4; ++rg) ss += O[m][rg] * O[m][rg];
;             ss += __shfl_xor(ss, 16, 64); ss += __shfl_xor(ss, 32, 64);
	v_mfma_f32_16x16x32_bf16 v[0:3], v[46:49], v[0:3], 0
	ds_read_b128 v[46:49], v33 offset:16192
	s_waitcnt lgkmcnt(0)
	v_mfma_f32_16x16x32_bf16 v[0:3], v[46:49], v[20:23], v[0:3]
	v_fmamk_f32 v20, v28, 0xc2e00000, v27
	v_fmamk_f32 v21, v26, 0x42e00000, v29
	v_cndmask_b32_e64 v20, v21, v20, s[16:17]
	v_exp_f32_e32 v20, v20
	s_nop 0
	v_cndmask_b32_e64 v20, v20, 2.0, s[18:19]
	s_nop 1
	v_mul_f32_e32 v33, v20, v0
	v_fmamk_f32 v0, v28, 0xc2e20000, v27
	v_fmamk_f32 v20, v26, 0x42e20000, v29
	v_cndmask_b32_e64 v0, v20, v0, s[20:21]
	v_exp_f32_e32 v0, v0
	s_nop 0
	v_cndmask_b32_e64 v0, v0, 2.0, s[22:23]
	v_mul_f32_e32 v46, v0, v1
	v_fmamk_f32 v0, v28, 0xc2e40000, v27
	v_fmamk_f32 v1, v26, 0x42e40000, v29
	v_cndmask_b32_e64 v0, v1, v0, s[24:25]
	v_exp_f32_e32 v0, v0
	v_fmac_f32_e32 v27, 0xc2e60000, v28
	v_fmac_f32_e32 v29, 0x42e60000, v26
	v_cndmask_b32_e64 v0, v0, 2.0, s[26:27]
	v_mul_f32_e32 v47, v0, v2
	v_cndmask_b32_e64 v0, v29, v27, s[28:29]
	v_exp_f32_e32 v0, v0
	s_nop 0
	v_cndmask_b32_e64 v0, v0, 2.0, s[30:31]
	v_mul_f32_e32 v26, v0, v3
	v_add_u32_e32 v20, 0x4800, v118
	v_cvt_pk_bf16_f32 v0, v30, v31
	v_cvt_pk_bf16_f32 v1, v32, v34
	v_cvt_pk_bf16_f32 v2, v35, v36
	v_cvt_pk_bf16_f32 v3, v38, v40
	ds_read2_b64 v[20:23], v20 offset1:4
	s_waitcnt lgkmcnt(0)
	v_mfma_f32_16x16x32_bf16 v[4:7], v[20:23], v[0:3], v[4:7]
	v_add_u32_e32 v20, 0x4800, v119
	ds_read2_b64 v[20:23], v20 offset1:4
	s_waitcnt lgkmcnt(0)
	v_mfma_f32_16x16x32_bf16 v[8:11], v[20:23], v[0:3], v[8:11]
	ds_read_b64 v[20:21], v120 offset:18432
	ds_read_b64 v[22:23], v121 offset:18432
	s_waitcnt lgkmcnt(0)
	v_mfma_f32_16x16x32_bf16 v[12:15], v[20:23], v[0:3], v[12:15]
	ds_read_b64 v[20:21], v122 offset:18432
	ds_read_b64 v[22:23], v123 offset:18432
	s_waitcnt lgkmcnt(0)
	v_mfma_f32_16x16x32_bf16 v[0:3], v[20:23], v[0:3], v[16:19]
	v_add_u32_e32 v20, 0x4800, v125
	v_cvt_pk_bf16_f32 v16, v37, v39
	v_cvt_pk_bf16_f32 v17, v41, v42
	v_cvt_pk_bf16_f32 v18, v43, v44
	v_cvt_pk_bf16_f32 v19, v45, v54
	ds_read2_b64 v[20:23], v20 offset1:4
	s_waitcnt lgkmcnt(0)
	v_mfma_f32_16x16x32_bf16 v[4:7], v[20:23], v[16:19], v[4:7]
	v_add_u32_e32 v20, 0x4800, v126
	ds_read2_b64 v[20:23], v20 offset1:4
	s_waitcnt lgkmcnt(0)
	v_mfma_f32_16x16x32_bf16 v[8:11], v[20:23], v[16:19], v[8:11]
	ds_read_b64 v[20:21], v127 offset:18432
	ds_read_b64 v[22:23], v128 offset:18432
	s_waitcnt lgkmcnt(0)
	v_mfma_f32_16x16x32_bf16 v[12:15], v[20:23], v[16:19], v[12:15]
	ds_read_b64 v[20:21], v129 offset:18432
	ds_read_b64 v[22:23], v130 offset:18432
	s_waitcnt lgkmcnt(0)
	v_mfma_f32_16x16x32_bf16 v[0:3], v[20:23], v[16:19], v[0:3]
	v_add_u32_e32 v20, 0x4800, v132
	v_cvt_pk_bf16_f32 v16, v55, v56
	v_cvt_pk_bf16_f32 v17, v57, v58
	v_cvt_pk_bf16_f32 v18, v59, v60
	v_cvt_pk_bf16_f32 v19, v61, v62
	ds_read2_b64 v[20:23], v20 offset1:4
	s_waitcnt lgkmcnt(0)
	v_mfma_f32_16x16x32_bf16 v[4:7], v[20:23], v[16:19], v[4:7]
	v_add_u32_e32 v20, 0x4800, v133
	ds_read2_b64 v[20:23], v20 offset1:4
	s_waitcnt lgkmcnt(0)
	v_mfma_f32_16x16x32_bf16 v[8:11], v[20:23], v[16:19], v[8:11]
	ds_read_b64 v[20:21], v134 offset:18432
	ds_read_b64 v[22:23], v135 offset:18432
	s_waitcnt lgkmcnt(0)
	v_mfma_f32_16x16x32_bf16 v[20:23], v[20:23], v[16:19], v[12:15]
	s_nop 2
	ds_read_b64 v[12:13], v136 offset:18432
	ds_read_b64 v[14:15], v137 offset:18432
	s_waitcnt lgkmcnt(0)
	v_mfma_f32_16x16x32_bf16 v[0:3], v[12:15], v[16:19], v[0:3]
	v_add_u32_e32 v12, 0x4800, v139
	v_cvt_pk_bf16_f32 v16, v50, v51
	v_cvt_pk_bf16_f32 v17, v52, v53
	v_cvt_pk_bf16_f32 v18, v33, v46
	v_cvt_pk_bf16_f32 v19, v47, v26
	ds_read2_b64 v[12:15], v12 offset1:4
	s_waitcnt lgkmcnt(0)
	v_mfma_f32_16x16x32_bf16 v[12:15], v[12:15], v[16:19], v[4:7]
	s_nop 2
	v_add_u32_e32 v4, 0x4800, v140
	ds_read2_b64 v[4:7], v4 offset1:4
	s_waitcnt lgkmcnt(0)
	v_mfma_f32_16x16x32_bf16 v[8:11], v[4:7], v[16:19], v[8:11]
	ds_read_b64 v[4:5], v141 offset:18432
	ds_read_b64 v[6:7], v142 offset:18432
	s_waitcnt lgkmcnt(0)
	v_mfma_f32_16x16x32_bf16 v[4:7], v[4:7], v[16:19], v[20:23]
	s_nop 2
	ds_read_b64 v[20:21], v143 offset:18432
	ds_read_b64 v[22:23], v154 offset:18432
	s_waitcnt lgkmcnt(0)
	v_mfma_f32_16x16x32_bf16 v[0:3], v[20:23], v[16:19], v[0:3]
	v_mul_f32_e32 v20, v13, v13
	v_fmac_f32_e32 v20, v12, v12
	v_fmac_f32_e32 v20, v14, v14
	v_fmac_f32_e32 v20, v15, v15
	v_fmac_f32_e32 v20, v8, v8
	v_fmac_f32_e32 v20, v9, v9
	v_fmac_f32_e32 v20, v10, v10
	v_fmac_f32_e32 v20, v11, v11
	v_pk_mul_f32 v[18:19], v[4:5], v[4:5]
	v_pk_mul_f32 v[16:17], v[6:7], v[6:7]
	v_add_f32_e32 v18, v18, v20
	v_add_f32_e32 v18, v19, v18
	v_add_f32_e32 v16, v16, v18
	v_add_f32_e32 v20, v17, v16
	v_pk_mul_f32 v[18:19], v[0:1], v[0:1]
	v_pk_mul_f32 v[16:17], v[2:3], v[2:3]
	v_add_f32_e32 v18, v18, v20
	v_add_f32_e32 v18, v19, v18
	v_add_f32_e32 v16, v16, v18
	v_and_b32_e32 v18, 64, v205
	v_add_f32_e32 v16, v17, v16
	v_xor_b32_e32 v17, 16, v205
	v_add_u32_e32 v18, 64, v18
	v_cmp_lt_i32_e32 vcc, v17, v18
	v_lshlrev_b32_e32 v20, 1, v86
	v_mov_b32_e32 v21, v145
	v_cndmask_b32_e32 v17, v205, v17, vcc
	v_lshlrev_b32_e32 v17, 2, v17
	ds_bpermute_b32 v17, v17, v16
	s_waitcnt lgkmcnt(0)
	v_add_f32_e32 v16, v16, v17
	v_xor_b32_e32 v17, 32, v205
	v_cmp_lt_i32_e32 vcc, v17, v18
	s_nop 1
	v_cndmask_b32_e32 v17, v205, v17, vcc
	v_lshlrev_b32_e32 v17, 2, v17
	ds_bpermute_b32 v17, v17, v16
	s_waitcnt lgkmcnt(0)
; __device__ __forceinline__ float bf2f(bf16_t b) { return __uint_as_float(((unsigned)b) << 16); }
; __device__ __forceinline__ float silu_f(float x) { return x * __builtin_amdgcn_rcpf(1.0f + __expf(-x)); }
; __device__ __forceinline__ unsigned cvt_pk_bf16(float lo, float hi) { unsigned r; asm volatile("v_cvt_pk_bf16_f32 %0, %1, %2" : "=v"(r) : "v"(lo), "v"(hi)); return r; }
; __device__ __forceinline__ void m3_outputs(const KQ p_in, int e, bool ctx_full, unsigned char* smem, unsigned* scan_word) {
;     ...
;             const float rn = rsqrtf(ss * (1.0f / 64.0f) + EPS);
; #pragma unroll
;             for (int m = 0; m < 4; ++m) {
;                 const int ee = 16 * m + 4 * g4;
;                 const bf16x4 gv = *(const bf16x4*)(Z + (size_t)(t0 + i) * INW + 1024 + h * 64 + ee);
;                 uint2 o2; o2.x = pg8::cvt_pk_bf16(O[m][0] * rn * silu_f(bf2f((bf16_t)gv[0])), O[m][1] * rn * silu_f(bf2f((bf16_t)gv[1])));
;                 o2.y = pg8::cvt_pk_bf16(O[m][2] * rn * silu_f(bf2f((bf16_t)gv[2])), O[m][3] * rn * silu_f(bf2f((bf16_t)gv[3])));
;                 *(uint2*)(MIX + (size_t)(t0 + i) * D + 512 + h * 64 + ee) = o2;
;             }
	v_add_f32_e32 v16, v16, v17
	v_fmamk_f32 v16, v16, 0x3c800000, v146
	v_cmp_gt_f32_e32 vcc, s67, v16
	v_mul_f32_e32 v17, 0x4b800000, v16
	s_nop 0
	v_cndmask_b32_e32 v16, v16, v17, vcc
	v_rsq_f32_e32 v16, v16
	s_nop 0
	v_mul_f32_e32 v17, 0x45800000, v16
	v_cndmask_b32_e32 v26, v16, v17, vcc
	v_lshlrev_b64 v[16:17], 11, v[106:107]
	v_lshl_add_u64 v[16:17], s[90:91], 0, v[16:17]
	v_lshl_add_u64 v[18:19], v[16:17], 0, s[80:81]
	v_lshl_add_u64 v[16:17], v[24:25], 0, v[20:21]
	global_load_dwordx2 v[22:23], v[16:17], off offset:2048
	global_load_dwordx2 v[28:29], v[16:17], off offset:2080
	global_load_dwordx2 v[30:31], v[16:17], off offset:2112
	global_load_dwordx2 v[32:33], v[16:17], off offset:2144
	v_mul_f32_e32 v12, v12, v26
	v_mul_f32_e32 v13, v13, v26
	v_mul_f32_e32 v8, v8, v26
	v_mul_f32_e32 v9, v9, v26
	v_mul_f32_e32 v4, v4, v26
	v_mul_f32_e32 v5, v5, v26
	v_mul_f32_e32 v0, v0, v26
	v_mul_f32_e32 v1, v1, v26
	s_waitcnt lgkmcnt(0)
	s_waitcnt vmcnt(0)
	v_lshlrev_b32_e32 v24, 16, v22
	v_mul_f32_e32 v25, 0xbfb8aa3b, v24
	v_exp_f32_e32 v25, v25
	v_and_b32_e32 v22, 0xffff0000, v22
	v_add_f32_e32 v25, 1.0, v25
	v_rcp_f32_e32 v25, v25
	s_nop 0
	v_mul_f32_e32 v24, v25, v24
	v_mul_f32_e32 v12, v24, v12
	v_mul_f32_e32 v24, 0xbfb8aa3b, v22
	v_exp_f32_e32 v24, v24
	s_nop 0
	v_add_f32_e32 v24, 1.0, v24
	v_rcp_f32_e32 v24, v24
	s_nop 0
	v_mul_f32_e32 v22, v24, v22
	v_mul_f32_e32 v13, v22, v13
	v_cvt_pk_bf16_f32 v22, v12, v13
	v_lshlrev_b32_e32 v13, 16, v23
	v_mul_f32_e32 v12, v14, v26
	v_mul_f32_e32 v14, 0xbfb8aa3b, v13
	v_exp_f32_e32 v14, v14
	s_nop 0
	v_add_f32_e32 v14, 1.0, v14
	v_rcp_f32_e32 v14, v14
	s_nop 0
	v_mul_f32_e32 v13, v14, v13
	v_and_b32_e32 v14, 0xffff0000, v23
	v_mul_f32_e32 v12, v13, v12
	v_mul_f32_e32 v13, v15, v26
	v_mul_f32_e32 v15, 0xbfb8aa3b, v14
	v_exp_f32_e32 v15, v15
	s_nop 0
	v_add_f32_e32 v15, 1.0, v15
	v_rcp_f32_e32 v15, v15
	s_nop 0
	v_mul_f32_e32 v14, v15, v14
	v_mul_f32_e32 v13, v14, v13
	v_cvt_pk_bf16_f32 v23, v12, v13
	v_mov_b32_e32 v14, v28
	v_mov_b32_e32 v15, v29
	v_lshl_add_u64 v[12:13], v[18:19], 0, v[20:21]
	global_store_dwordx2 v[12:13], v[22:23], off offset:1024
	s_waitcnt lgkmcnt(0)
	s_waitcnt vmcnt(1)
	v_lshlrev_b32_e32 v18, 16, v14
	v_mul_f32_e32 v19, 0xbfb8aa3b, v18
	v_exp_f32_e32 v19, v19
	v_and_b32_e32 v14, 0xffff0000, v14
	v_add_f32_e32 v19, 1.0, v19
	v_rcp_f32_e32 v19, v19
	s_nop 0
	v_mul_f32_e32 v18, v19, v18
	v_mul_f32_e32 v8, v8, v18
	v_mul_f32_e32 v18, 0xbfb8aa3b, v14
	v_exp_f32_e32 v18, v18
	s_nop 0
	v_add_f32_e32 v18, 1.0, v18
	v_rcp_f32_e32 v18, v18
	s_nop 0
	v_mul_f32_e32 v14, v18, v14
	v_mul_f32_e32 v9, v9, v14
	v_cvt_pk_bf16_f32 v8, v8, v9
	v_mul_f32_e32 v9, v10, v26
	v_lshlrev_b32_e32 v10, 16, v15
	v_mul_f32_e32 v14, 0xbfb8aa3b, v10
	v_exp_f32_e32 v14, v14
	s_nop 0
	v_add_f32_e32 v14, 1.0, v14
	v_rcp_f32_e32 v14, v14
	s_nop 0
	v_mul_f32_e32 v10, v14, v10
	v_mul_f32_e32 v9, v9, v10
	v_mul_f32_e32 v10, v11, v26
	v_and_b32_e32 v11, 0xffff0000, v15
	v_mul_f32_e32 v14, 0xbfb8aa3b, v11
	v_exp_f32_e32 v14, v14
	s_nop 0
	v_add_f32_e32 v14, 1.0, v14
	v_rcp_f32_e32 v14, v14
	s_nop 0
	v_mul_f32_e32 v11, v14, v11
	v_mul_f32_e32 v10, v10, v11
	v_cvt_pk_bf16_f32 v9, v9, v10
	global_store_dwordx2 v[12:13], v[8:9], off offset:1056
	v_mov_b32_e32 v8, v30
	v_mov_b32_e32 v9, v31
	s_waitcnt lgkmcnt(0)
	s_waitcnt vmcnt(0)
	v_lshlrev_b32_e32 v10, 16, v8
	v_mul_f32_e32 v11, 0xbfb8aa3b, v10
	v_exp_f32_e32 v11, v11
	v_and_b32_e32 v8, 0xffff0000, v8
	v_add_f32_e32 v11, 1.0, v11
	v_rcp_f32_e32 v11, v11
	s_nop 0
	v_mul_f32_e32 v10, v11, v10
	v_mul_f32_e32 v4, v4, v10
	v_mul_f32_e32 v10, 0xbfb8aa3b, v8
	v_exp_f32_e32 v10, v10
	s_nop 0
	v_add_f32_e32 v10, 1.0, v10
	v_rcp_f32_e32 v10, v10
	s_nop 0
	v_mul_f32_e32 v8, v10, v8
	v_mul_f32_e32 v5, v5, v8
	v_cvt_pk_bf16_f32 v4, v4, v5
	v_mul_f32_e32 v5, v6, v26
	v_lshlrev_b32_e32 v6, 16, v9
	v_mul_f32_e32 v8, 0xbfb8aa3b, v6
	v_exp_f32_e32 v8, v8
	s_nop 0
	v_add_f32_e32 v8, 1.0, v8
	v_rcp_f32_e32 v8, v8
	s_nop 0
	v_mul_f32_e32 v6, v8, v6
	v_mul_f32_e32 v5, v5, v6
	v_mul_f32_e32 v6, v7, v26
	v_and_b32_e32 v7, 0xffff0000, v9
	v_mul_f32_e32 v8, 0xbfb8aa3b, v7
	v_exp_f32_e32 v8, v8
	s_nop 0
	v_add_f32_e32 v8, 1.0, v8
	v_rcp_f32_e32 v8, v8
	s_nop 0
	v_mul_f32_e32 v7, v8, v7
	v_mul_f32_e32 v6, v6, v7
	v_cvt_pk_bf16_f32 v5, v5, v6
	global_store_dwordx2 v[12:13], v[4:5], off offset:1088
	v_mov_b32_e32 v4, v32
	v_mov_b32_e32 v5, v33
	s_waitcnt lgkmcnt(0)
	s_waitcnt vmcnt(0)
	v_lshlrev_b32_e32 v6, 16, v4
	v_mul_f32_e32 v7, 0xbfb8aa3b, v6
	v_exp_f32_e32 v7, v7
	v_and_b32_e32 v4, 0xffff0000, v4
	v_add_f32_e32 v7, 1.0, v7
	v_rcp_f32_e32 v7, v7
	s_nop 0
	v_mul_f32_e32 v6, v7, v6
	v_mul_f32_e32 v0, v0, v6
	v_mul_f32_e32 v6, 0xbfb8aa3b, v4
	v_exp_f32_e32 v6, v6
	s_nop 0
	v_add_f32_e32 v6, 1.0, v6
	v_rcp_f32_e32 v6, v6
	s_nop 0
	v_mul_f32_e32 v4, v6, v4
	v_mul_f32_e32 v1, v1, v4
	v_cvt_pk_bf16_f32 v0, v0, v1
	v_mul_f32_e32 v1, v2, v26
	v_lshlrev_b32_e32 v2, 16, v5
	v_mul_f32_e32 v4, 0xbfb8aa3b, v2
	v_exp_f32_e32 v4, v4
	s_nop 0
	v_add_f32_e32 v4, 1.0, v4
	v_rcp_f32_e32 v4, v4
	s_nop 0
	v_mul_f32_e32 v2, v4, v2
	v_mul_f32_e32 v1, v1, v2
	v_mul_f32_e32 v2, v3, v26
	v_and_b32_e32 v3, 0xffff0000, v5
	v_mul_f32_e32 v4, 0xbfb8aa3b, v3
	v_exp_f32_e32 v4, v4
	s_nop 0
	v_add_f32_e32 v4, 1.0, v4
	v_rcp_f32_e32 v4, v4
	s_nop 0
	v_mul_f32_e32 v3, v4, v3
	v_mul_f32_e32 v2, v2, v3
	v_cvt_pk_bf16_f32 v1, v1, v2
	global_store_dwordx2 v[12:13], v[0:1], off offset:1120
	s_cbranch_execnz .LBB0_933
	s_branch .LBB0_963
